# P0: half of WGs (blockIdx bit3) run weight transposes before x conversion; moba gating loop rewritten (pipelined LDS reads, DPP pair-sum, branch-free top3)
# speedup vs baseline: 1.0055x; 1.0055x over previous
; DI u32x2 pk4(f32x4 v) { u32x2 r; r.x = pk2(v[0], v[1]); r.y = pk2(v[2], v[3]); return r; }
;   unsigned char* ws = p.ws;
;   const long gtid = (long)blockIdx.x * NTHREADS + threadIdx.x, nthr = (long)gridDim.x * NTHREADS;
;   const int lane = threadIdx.x & 63, wv = threadIdx.x >> 6, gw = blockIdx.x * 8 + wv, ngw = gridDim.x * 8;
;   if (part & 1) {
;     bf16_t* xb = (bf16_t*)((unsigned char*)p.out + 64 * MiB);
;     float* rstd1 = (float*)(ws + OFF_RSTD1);
;     for (int r0 = gw * 8; r0 < T_TOK; r0 += ngw * 8) {
;       f32x4 v[8][4];
; #pragma unroll
;       for (int rr = 0; rr < 8; ++rr) {
;         const f32x4* xr = (const f32x4*)(p.x + (long)(r0 + rr) * DM) + lane;
; #pragma unroll
;         for (int j = 0; j < 4; ++j) v[rr][j] = xr[64 * j];
;       }
; #pragma unroll
;       for (int rr = 0; rr < 8; ++rr) {
;         float s = 0.f;
; #pragma unroll
;         for (int j = 0; j < 4; ++j) s += v[rr][j][0] * v[rr][j][0] + v[rr][j][1] * v[rr][j][1] + v[rr][j][2] * v[rr][j][2] + v[rr][j][3] * v[rr][j][3];
; #pragma unroll
;         for (int o = 1; o < 64; o <<= 1) s += __shfl_xor(s, o);
;         if (lane == 0) { const float rv = 1.0f / sqrtf(s * (1.0f / DM) + 1e-6f); const int r = r0 + rr, rl = r & 255;
;           rstd1[r] = rv; ((float*)(ws + OFF_RSTD1Q))[(r & ~255) + (((rl >> 6) & 1) * 16 + (rl & 15)) * 8 + (rl >> 7) * 4 + ((rl >> 4) & 3)] = rv; }
;         u32x2* o8 = (u32x2*)(xb + (long)(r0 + rr) * DM) + lane;
; #pragma unroll
;         for (int j = 0; j < 4; ++j) o8[64 * j] = pk4(v[rr][j]);
.LBB0_5:
	s_or_b64 exec, exec, s[0:1]
	v_lshrrev_b32_e32 v140, 6, v194
	v_lshl_add_u32 v139, s2, 3, v140
	s_movk_i32 s0, 0x1000
	v_and_b32_e32 v138, 63, v194
	s_mov_b32 s99, 0
	s_bitcmp1_b32 s2, 3
	s_cbranch_scc1 .Lp0_W
.Lp0_X:
	v_cmp_gt_i32_e32 vcc, s0, v139
	s_and_saveexec_b64 s[16:17], vcc
	s_cbranch_execz .LBB0_24
	v_mbcnt_lo_u32_b32 v1, -1, 0
	v_mbcnt_hi_u32_b32 v2, -1, v1
	v_and_b32_e32 v1, 64, v2
	v_add_u32_e32 v3, 64, v1
	v_xor_b32_e32 v1, 1, v2
	v_cmp_lt_i32_e32 vcc, v1, v3
	v_xor_b32_e32 v4, 2, v2
	v_lshlrev_b32_e32 v130, 3, v139
	v_cndmask_b32_e32 v1, v2, v1, vcc
	v_cmp_lt_i32_e32 vcc, v4, v3
	v_ashrrev_i32_e32 v131, 31, v130
	s_mov_b64 s[0:1], 0x1e70001c
	v_cndmask_b32_e32 v4, v2, v4, vcc
	v_lshlrev_b32_e32 v141, 2, v4
	v_xor_b32_e32 v4, 4, v2
	v_cmp_lt_i32_e32 vcc, v4, v3
	s_add_u32 s20, s26, 0x1e7e5000
	s_addc_u32 s21, s27, 0
	v_cndmask_b32_e32 v4, v2, v4, vcc
	v_lshlrev_b32_e32 v142, 2, v4
	v_xor_b32_e32 v4, 8, v2
	v_cmp_lt_i32_e32 vcc, v4, v3
	s_lshl_b32 s22, s28, 6
	s_ashr_i32 s23, s22, 31
	v_cndmask_b32_e32 v4, v2, v4, vcc
	v_lshlrev_b32_e32 v143, 2, v4
	v_xor_b32_e32 v4, 16, v2
	v_cmp_lt_i32_e32 vcc, v4, v3
	v_cmp_eq_u32_e64 s[4:5], 0, v138
	v_lshlrev_b32_e32 v1, 2, v1
	v_cndmask_b32_e32 v4, v2, v4, vcc
	v_lshlrev_b32_e32 v144, 2, v4
	v_xor_b32_e32 v4, 32, v2
	v_cmp_lt_i32_e32 vcc, v4, v3
	s_lshl_b64 s[34:35], s[22:23], 2
	s_lshl_b64 s[52:53], s[22:23], 11
	v_cndmask_b32_e32 v2, v2, v4, vcc
	v_lshlrev_b32_e32 v145, 2, v2
	v_lshl_add_u64 v[2:3], v[130:131], 2, s[26:27]
	v_lshl_add_u64 v[132:133], v[2:3], 0, s[0:1]
	v_lshlrev_b64 v[2:3], 11, v[130:131]
	v_lshl_or_b32 v2, v138, 3, v2
	v_lshl_add_u64 v[2:3], s[24:25], 0, v[2:3]
	s_mov_b64 s[0:1], 0x4003e00
	v_lshl_add_u64 v[134:135], v[2:3], 0, s[0:1]
	v_lshlrev_b64 v[2:3], 12, v[130:131]
	v_lshl_or_b32 v2, v138, 4, v2
	v_lshl_add_u64 v[2:3], s[36:37], 0, v[2:3]
	s_mov_b64 s[0:1], 0x7c00
	v_lshl_add_u64 v[136:137], v[2:3], 0, s[0:1]
	s_lshl_b64 s[54:55], s[22:23], 12
	s_mov_b64 s[56:57], 0
	v_mov_b32_e32 v131, 0x358637bd
	s_mov_b32 s3, 0xf800000
	v_mov_b32_e32 v146, 0x260
	s_movk_i32 s18, 0x7fff
	s_branch .LBB0_8

; #define LAS __attribute__((address_space(3)))
;     ...
;   if (part & 2) {
;     LAS float* scr = (LAS float*)shm + wv * (64 * 33);
;     constexpr int I0 = 16 * 208, I1 = 16 * 32, I2 = 8 * 32, I3 = 16 * 32, I4 = 16 * 176, I5 = 44 * 32;
;     for (int it = gw; it < I0 + I1 + I2 + I3 + I4 + I5; it += ngw) {
;       int r = it;
;       if (r < I0) { conv_item<0>(p.w_in, nullptr, p.norm1_w, (bf16_t*)(ws + OFF_WIN), 1024, NCOL, 208, scr, r, lane); continue; } r -= I0;
;       if (r < I1) { conv_item<3>(p.w_ret_out, nullptr, nullptr, (bf16_t*)(ws + OFF_WRO), 1024, 1024, 32, scr, r, lane); continue; } r -= I1;
;       if (r < I2) { conv_item<3>(p.w_moba_out, nullptr, nullptr, (bf16_t*)(ws + OFF_WMO), 512, 1024, 32, scr, r, lane); continue; } r -= I2;
;       if (r < I3) { conv_item<3>(p.w_o, nullptr, nullptr, (bf16_t*)(ws + OFF_WO), 1024, 1024, 32, scr, r, lane); continue; } r -= I3;
;       if (r < I4) { conv_item<1>(p.w_gate, p.w_up, p.norm2_w, (bf16_t*)(ws + OFF_WGU), 1024, FH, 176, scr, r, lane); continue; } r -= I4;
;       conv_item<2>(p.w_down, nullptr, nullptr, (bf16_t*)(ws + OFF_WD), FH, 1024, 32, scr, r, lane);
;     }
.LBB0_24:
	s_or_b64 exec, exec, s[16:17]
	s_cmp_eq_u32 s99, 1
	s_cbranch_scc1 .Lp0_tail
.Lp0_W:
	s_movk_i32 s0, 0x2280
	v_cmp_gt_i32_e32 vcc, s0, v139
	s_and_saveexec_b64 s[16:17], vcc
	v_writelane_b32 v250, s96, 1
	s_nop 1
	v_writelane_b32 v250, s97, 2
	v_writelane_b32 v250, s94, 3
	s_nop 1
	v_writelane_b32 v250, s95, 4
	s_cbranch_execz .LBB0_99
	v_lshlrev_b32_e32 v6, 3, v194
	v_and_b32_e32 v6, 56, v6
	s_movk_i32 s4, 0x2100
	v_and_b32_e32 v3, 31, v194
	v_lshrrev_b32_e32 v5, 3, v138
	v_mul_u32_u24_e32 v12, 0x84, v6
	v_lshlrev_b32_e32 v6, 1, v6
	v_mov_b32_e32 v7, 0
	v_mad_u32_u24 v1, v140, s4, 0
	v_lshlrev_b32_e32 v20, 2, v3
	v_lshl_add_u64 v[8:9], s[26:27], 0, v[6:7]
	v_lshlrev_b32_e32 v6, 2, v5
	v_add_u32_e32 v4, v1, v20
	s_mov_b64 s[0:1], 0x1d00000
	v_add3_u32 v40, v1, v12, v6
	v_lshlrev_b32_e32 v1, 1, v194
	s_lshl_b32 s3, s28, 3
	v_lshl_add_u64 v[10:11], v[8:9], 0, s[0:1]
	v_and_b32_e32 v6, 24, v1
	v_lshrrev_b32_e32 v1, 2, v194
	s_mov_b64 s[0:1], 0x1200000
	v_lshrrev_b32_e32 v2, 5, v138
	v_and_b32_e32 v21, 4, v1
	v_lshl_add_u64 v[12:13], v[8:9], 0, s[0:1]
	s_mov_b64 s[0:1], 0x1000000
	v_and_b32_e32 v1, 15, v194
	v_lshlrev_b32_e32 v23, 2, v194
	s_cmp_lg_u64 s[8:9], 0
	v_lshl_add_u64 v[14:15], v[8:9], 0, s[0:1]
	s_mov_b64 s[0:1], 0xf00000
	v_and_or_b32 v46, v23, 64, v1
	s_cselect_b64 s[34:35], -1, 0
	s_cmp_lg_u64 s[38:39], 0
	v_mul_u32_u24_e32 v23, 0x84, v2
	v_and_b32_e32 v22, 3, v194
	v_lshl_add_u64 v[16:17], v[8:9], 0, s[0:1]
	s_mov_b64 s[0:1], 0xd00000
	s_cselect_b64 s[52:53], -1, 0
	v_mad_u32_u24 v23, v140, s4, v23
	s_add_u32 s40, s40, 0x34000
	s_mov_b32 s21, 0
	s_movk_i32 s18, 0x84
	v_or_b32_e32 v41, 8, v5
	v_or_b32_e32 v42, 16, v5
	v_or_b32_e32 v43, 24, v5
	v_or3_b32 v44, v6, v22, v21
	v_or3_b32 v45, v21, v22, v6
	s_waitcnt lgkmcnt(0)
	v_lshl_add_u64 v[18:19], v[8:9], 0, s[0:1]
	s_mov_b64 s[22:23], 0
	v_mov_b32_e32 v1, v2
	v_add3_u32 v47, v23, v20, 0
	v_or_b32_e32 v48, 14, v2
	v_or_b32_e32 v49, 12, v2
	v_or_b32_e32 v50, 10, v2
	v_or_b32_e32 v51, 8, v2
	v_or_b32_e32 v52, 6, v2
	v_or_b32_e32 v53, 4, v2
	v_or_b32_e32 v54, 2, v2
	v_or3_b32 v55, v6, v21, v22
	s_addc_u32 s41, s41, 0
	s_movk_i32 s19, 0x11ff
	s_movk_i32 s30, 0x3ff
	s_movk_i32 s31, 0xf00
	s_movk_i32 s70, 0x1ff
	s_movk_i32 s71, 0x6800
	s_mov_b64 s[54:55], 0x68000
	s_movk_i32 s72, 0x227f
	v_mov_b32_e32 v56, 0x3db504f3
	s_branch .LBB0_28

;     ...
;   if (part & 1) {
;     bf16_t* xb = (bf16_t*)((unsigned char*)p.out + 64 * MiB);
;     float* rstd1 = (float*)(ws + OFF_RSTD1);
;     for (int r0 = gw * 8; r0 < T_TOK; r0 += ngw * 8) {
;     ...
;   if (part & 4) {
;     float* cosT = (float*)(ws + OFF_COS); float* sinT = (float*)(ws + OFF_SIN);
;     for (long idx = gtid; idx < (long)SEQ * 64; idx += nthr) {
;       const int pos = (int)(idx >> 6), j = (int)(idx & 63);
;       const float inv = exp2f(-(float)j * (13.287712379549449f / 64.0f));
;       const float ang = (float)pos * inv;
;       const double rev = (double)ang * 0.15915494309189535;
;       const float fr = (float)(rev - __builtin_rint(rev));
;       cosT[idx] = __builtin_amdgcn_cosf(fr); sinT[idx] = __builtin_amdgcn_sinf(fr);
.LBB0_99:
	s_or_b64 exec, exec, s[16:17]
	s_bitcmp1_b32 s2, 3
	s_cbranch_scc0 .Lp0_tail
	s_cmp_eq_u32 s99, 1
	s_cbranch_scc1 .Lp0_tail
	s_mov_b32 s99, 1
	v_lshl_add_u32 v139, s2, 3, v140
	s_movk_i32 s0, 0x1000
	s_branch .Lp0_X
.Lp0_tail:
	s_mov_b32 s3, 0
	s_lshl_b64 s[0:1], s[2:3], 9
	v_mov_b32_e32 v195, 0
	v_lshl_add_u64 v[2:3], s[0:1], 0, v[194:195]
	s_mov_b64 s[0:1], 0x80000
	v_cmp_gt_u64_e32 vcc, s[0:1], v[2:3]
	s_and_saveexec_b64 s[0:1], vcc
	s_cbranch_execz .LBB0_102
	v_cvt_f32_ubyte0_e32 v1, v138
	v_mul_f32_e32 v4, 0xbe549a78, v1
	s_mov_b32 s4, 0xc2fc0000
	v_not_b32_e32 v5, 63
	v_cmp_gt_f32_e32 vcc, s4, v4
	s_mov_b32 s8, s28
	s_mov_b32 s9, s3
	v_cndmask_b32_e32 v4, 0, v5, vcc
	v_mov_b32_e32 v5, 0x42800000
	v_cndmask_b32_e32 v5, 0, v5, vcc
	v_fmac_f32_e32 v5, 0xbe549a78, v1
	v_exp_f32_e32 v1, v5
	s_lshl_b64 s[4:5], s[8:9], 9
	s_lshl_b64 s[10:11], s[2:3], 11
	s_add_u32 s10, s26, s10
	v_ldexp_f32 v1, v1, v4
	v_lshlrev_b32_e32 v4, 2, v194
	v_mov_b32_e32 v5, v195
	s_addc_u32 s11, s27, s11
	v_lshl_add_u64 v[4:5], s[10:11], 0, v[4:5]
	s_mov_b64 s[10:11], 0x1e300000
	s_mov_b32 s12, 0x6dc9c883
	v_lshl_add_u64 v[4:5], v[4:5], 0, s[10:11]
	s_lshl_b64 s[8:9], s[8:9], 11
	s_mov_b64 s[10:11], 0
	s_mov_b32 s13, 0x3fc45f30
	s_mov_b64 s[14:15], 0x7ffff

; #define LAS __attribute__((address_space(3)))
;     ...
;       const u32x4* qp = (const u32x4*)(Mq + qbase + (long)qt * 64 + qh * 32);
; #pragma unroll
;       for (int i = 0; i < 4; ++i) { qw[i] = qp[i]; *(LAS u32x4*)(Qs + qt * MO_QS + qh * 64 + i * 16) = qw[i]; }
;     }
;     __syncthreads();
;     if (blk > 0) {
;       float q[32];
; #pragma unroll
;       for (int i = 0; i < 4; ++i) { const u32x4 w4 = qw[i]; q[8 * i] = __uint_as_float(w4.x << 16); q[8 * i + 1] = __uint_as_float(w4.x & 0xffff0000u); q[8 * i + 2] = __uint_as_float(w4.y << 16); q[8 * i + 3] = __uint_as_float(w4.y & 0xffff0000u);
;         q[8 * i + 4] = __uint_as_float(w4.z << 16); q[8 * i + 5] = __uint_as_float(w4.z & 0xffff0000u); q[8 * i + 6] = __uint_as_float(w4.w << 16); q[8 * i + 7] = __uint_as_float(w4.w & 0xffff0000u); }
;       float v0 = -3e38f, v1 = -3e38f, v2 = -3e38f; int i0 = -1, i1 = -1, i2 = -1;
;       for (int j = 0; j < blk; ++j) {
;         float g0 = 0.f, g1 = 0.f;
; #pragma unroll
;         for (int d = 0; d < 32; d += 8) { const f32x4 k4 = *(const LAS f32x4*)(kb + j * 64 + qh * 32 + d), k5 = *(const LAS f32x4*)(kb + j * 64 + qh * 32 + d + 4);
;           g0 += q[d] * k4[0] + q[d + 1] * k4[1] + q[d + 2] * k4[2] + q[d + 3] * k4[3]; g1 += q[d + 4] * k5[0] + q[d + 5] * k5[1] + q[d + 6] * k5[2] + q[d + 7] * k5[3]; }
;         float g = g0 + g1;
;         g += __shfl_xor(g, 1);
;         if (g > v0) { v2 = v1; i2 = i1; v1 = v0; i1 = i0; v0 = g; i0 = j; }
;         else if (g > v1) { v2 = v1; i2 = i1; v1 = g; i1 = j; }
;         else if (g > v2) { v2 = g; i2 = j; }
;       }
.LBB0_573:
	s_or_b64 exec, exec, s[16:17]
	s_lshl_b32 s16, s18, 8
	s_ashr_i32 s17, s16, 31
	s_add_u32 s16, s50, s16
	s_addc_u32 s17, s51, s17
	s_lshl_b64 s[16:17], s[16:17], 7
	v_lshl_add_u64 v[198:199], v[190:191], 0, s[16:17]
	global_load_dwordx4 v[14:17], v[198:199], off
	global_load_dwordx4 v[10:13], v[198:199], off offset:16
	global_load_dwordx4 v[6:9], v[198:199], off offset:32
	global_load_dwordx4 v[2:5], v[198:199], off offset:48
	s_cmp_gt_i32 s18, 0
	s_waitcnt vmcnt(3)
	ds_write_b128 v186, v[14:17]
	s_waitcnt vmcnt(2)
	ds_write_b128 v186, v[10:13] offset:16
	s_waitcnt vmcnt(1)
	ds_write_b128 v186, v[6:9] offset:32
	s_waitcnt vmcnt(0)
	ds_write_b128 v186, v[2:5] offset:48
	s_waitcnt lgkmcnt(0)
	s_barrier
	s_cbranch_scc0 .LBB0_589
	v_lshlrev_b32_e32 v100, 16, v14
	v_and_b32_e32 v101, 0xffff0000, v14
	v_lshlrev_b32_e32 v102, 16, v15
	v_and_b32_e32 v103, 0xffff0000, v15
	v_lshlrev_b32_e32 v104, 16, v16
	v_and_b32_e32 v105, 0xffff0000, v16
	v_lshlrev_b32_e32 v106, 16, v17
	v_and_b32_e32 v107, 0xffff0000, v17
	v_lshlrev_b32_e32 v108, 16, v10
	v_and_b32_e32 v109, 0xffff0000, v10
	v_lshlrev_b32_e32 v110, 16, v11
	v_and_b32_e32 v111, 0xffff0000, v11
	v_lshlrev_b32_e32 v112, 16, v12
	v_and_b32_e32 v113, 0xffff0000, v12
	v_lshlrev_b32_e32 v114, 16, v13
	v_and_b32_e32 v115, 0xffff0000, v13
	v_lshlrev_b32_e32 v116, 16, v6
	v_and_b32_e32 v117, 0xffff0000, v6
	v_lshlrev_b32_e32 v118, 16, v7
	v_and_b32_e32 v119, 0xffff0000, v7
	v_lshlrev_b32_e32 v120, 16, v8
	v_and_b32_e32 v121, 0xffff0000, v8
	v_lshlrev_b32_e32 v122, 16, v9
	v_and_b32_e32 v123, 0xffff0000, v9
	v_lshlrev_b32_e32 v124, 16, v2
	v_and_b32_e32 v125, 0xffff0000, v2
	v_lshlrev_b32_e32 v126, 16, v3
	v_and_b32_e32 v127, 0xffff0000, v3
	v_lshlrev_b32_e32 v128, 16, v4
	v_and_b32_e32 v129, 0xffff0000, v4
	v_lshlrev_b32_e32 v130, 16, v5
	v_and_b32_e32 v131, 0xffff0000, v5
	v_mov_b32_e32 v132, 0xff61b1e6
	v_mov_b32_e32 v133, 0xff61b1e6
	v_mov_b32_e32 v134, 0xff61b1e6
	v_mov_b32_e32 v135, -1
	v_mov_b32_e32 v136, -1
	v_mov_b32_e32 v137, -1
	s_mov_b32 s19, 0
	v_mov_b32_e32 v3, v231
	ds_read_b128 v[36:39], v3 offset:0
	ds_read_b128 v[40:43], v3 offset:16
	ds_read_b128 v[44:47], v3 offset:32
	ds_read_b128 v[48:51], v3 offset:48
	ds_read_b128 v[52:55], v3 offset:64
	ds_read_b128 v[56:59], v3 offset:80
	ds_read_b128 v[60:63], v3 offset:96
	ds_read_b128 v[64:67], v3 offset:112
.Lg_loop:
	s_waitcnt lgkmcnt(0)
	ds_read_b128 v[68:71], v3 offset:256
	ds_read_b128 v[72:75], v3 offset:272
	ds_read_b128 v[76:79], v3 offset:288
	ds_read_b128 v[80:83], v3 offset:304
	ds_read_b128 v[84:87], v3 offset:320
	ds_read_b128 v[88:91], v3 offset:336
	ds_read_b128 v[92:95], v3 offset:352
	ds_read_b128 v[96:99], v3 offset:368
	v_pk_mul_f32 v[138:139], v[100:101], v[36:37]
	v_pk_mul_f32 v[140:141], v[102:103], v[38:39]
	v_pk_fma_f32 v[138:139], v[104:105], v[40:41], v[138:139]
	v_pk_fma_f32 v[140:141], v[106:107], v[42:43], v[140:141]
	v_pk_fma_f32 v[138:139], v[108:109], v[44:45], v[138:139]
	v_pk_fma_f32 v[140:141], v[110:111], v[46:47], v[140:141]
	v_pk_fma_f32 v[138:139], v[112:113], v[48:49], v[138:139]
	v_pk_fma_f32 v[140:141], v[114:115], v[50:51], v[140:141]
	v_pk_fma_f32 v[138:139], v[116:117], v[52:53], v[138:139]
	v_pk_fma_f32 v[140:141], v[118:119], v[54:55], v[140:141]
	v_pk_fma_f32 v[138:139], v[120:121], v[56:57], v[138:139]
	v_pk_fma_f32 v[140:141], v[122:123], v[58:59], v[140:141]
	v_pk_fma_f32 v[138:139], v[124:125], v[60:61], v[138:139]
	v_pk_fma_f32 v[140:141], v[126:127], v[62:63], v[140:141]
	v_pk_fma_f32 v[138:139], v[128:129], v[64:65], v[138:139]
	v_pk_fma_f32 v[140:141], v[130:131], v[66:67], v[140:141]
	v_pk_add_f32 v[138:139], v[138:139], v[140:141]
	v_mov_b32_e32 v143, s19
	v_add_f32_e32 v142, v138, v139
	s_nop 1
	v_add_f32_dpp v142, v142, v142 quad_perm:[1,0,3,2] row_mask:0xf bank_mask:0xf
	v_cmp_gt_f32_e32 vcc, v142, v134
	v_cmp_gt_f32_e64 s[52:53], v142, v133
	v_cmp_gt_f32_e64 s[22:23], v142, v132
	s_add_i32 s19, s19, 1
	v_cndmask_b32_e32 v134, v134, v142, vcc
	v_cndmask_b32_e32 v137, v137, v143, vcc
	v_cndmask_b32_e64 v134, v134, v133, s[52:53]
	v_cndmask_b32_e64 v137, v137, v136, s[52:53]
	v_cndmask_b32_e64 v133, v133, v142, s[52:53]
	v_cndmask_b32_e64 v136, v136, v143, s[52:53]
	v_cndmask_b32_e64 v133, v133, v132, s[22:23]
	v_cndmask_b32_e64 v136, v136, v135, s[22:23]
	v_cndmask_b32_e64 v132, v132, v142, s[22:23]
	v_cndmask_b32_e64 v135, v135, v143, s[22:23]
	v_add_u32_e32 v3, 0x100, v3
	s_cmp_eq_u32 s19, s18
	s_cbranch_scc1 .Lg_done
	s_waitcnt lgkmcnt(0)
	ds_read_b128 v[36:39], v3 offset:256
	ds_read_b128 v[40:43], v3 offset:272
	ds_read_b128 v[44:47], v3 offset:288
	ds_read_b128 v[48:51], v3 offset:304
	ds_read_b128 v[52:55], v3 offset:320
	ds_read_b128 v[56:59], v3 offset:336
	ds_read_b128 v[60:63], v3 offset:352
	ds_read_b128 v[64:67], v3 offset:368
	v_pk_mul_f32 v[138:139], v[100:101], v[68:69]
	v_pk_mul_f32 v[140:141], v[102:103], v[70:71]
	v_pk_fma_f32 v[138:139], v[104:105], v[72:73], v[138:139]
	v_pk_fma_f32 v[140:141], v[106:107], v[74:75], v[140:141]
	v_pk_fma_f32 v[138:139], v[108:109], v[76:77], v[138:139]
	v_pk_fma_f32 v[140:141], v[110:111], v[78:79], v[140:141]
	v_pk_fma_f32 v[138:139], v[112:113], v[80:81], v[138:139]
	v_pk_fma_f32 v[140:141], v[114:115], v[82:83], v[140:141]
	v_pk_fma_f32 v[138:139], v[116:117], v[84:85], v[138:139]
	v_pk_fma_f32 v[140:141], v[118:119], v[86:87], v[140:141]
	v_pk_fma_f32 v[138:139], v[120:121], v[88:89], v[138:139]
	v_pk_fma_f32 v[140:141], v[122:123], v[90:91], v[140:141]
	v_pk_fma_f32 v[138:139], v[124:125], v[92:93], v[138:139]
	v_pk_fma_f32 v[140:141], v[126:127], v[94:95], v[140:141]
	v_pk_fma_f32 v[138:139], v[128:129], v[96:97], v[138:139]
	v_pk_fma_f32 v[140:141], v[130:131], v[98:99], v[140:141]
	v_pk_add_f32 v[138:139], v[138:139], v[140:141]
	v_mov_b32_e32 v143, s19
	v_add_f32_e32 v142, v138, v139
	s_nop 1
	v_add_f32_dpp v142, v142, v142 quad_perm:[1,0,3,2] row_mask:0xf bank_mask:0xf
	v_cmp_gt_f32_e32 vcc, v142, v134
	v_cmp_gt_f32_e64 s[52:53], v142, v133
	v_cmp_gt_f32_e64 s[22:23], v142, v132
	s_add_i32 s19, s19, 1
	v_cndmask_b32_e32 v134, v134, v142, vcc
	v_cndmask_b32_e32 v137, v137, v143, vcc
	v_cndmask_b32_e64 v134, v134, v133, s[52:53]
	v_cndmask_b32_e64 v137, v137, v136, s[52:53]
	v_cndmask_b32_e64 v133, v133, v142, s[52:53]
	v_cndmask_b32_e64 v136, v136, v143, s[52:53]
	v_cndmask_b32_e64 v133, v133, v132, s[22:23]
	v_cndmask_b32_e64 v136, v136, v135, s[22:23]
	v_cndmask_b32_e64 v132, v132, v142, s[22:23]
	v_cndmask_b32_e64 v135, v135, v143, s[22:23]
	v_add_u32_e32 v3, 0x100, v3
	s_cmp_eq_u32 s19, s18
	s_cbranch_scc0 .Lg_loop
.Lg_done:
	s_waitcnt lgkmcnt(0)
	v_mov_b32_e32 v43, v135
	v_mov_b32_e32 v41, v136
	v_mov_b32_e32 v1, v137
